# pk_mov peephole extended to the rest of the kernel (44 more adjacent v_mov pairs, same code size)
# baseline (speedup 1.0000x reference)
.LBB0_28:
	s_mul_hi_i32 s6, s10, 0x2aaaaaab
	s_lshr_b32 s7, s6, 31
	s_ashr_i32 s11, s6, 3
	s_add_i32 s11, s11, s7
	s_mul_i32 s6, s11, 48
	s_sub_i32 s6, s10, s6
	s_mul_i32 s8, s11, 0x1800000
	s_lshl_b32 s6, s6, 7
	s_mul_hi_i32 s7, s11, 0x1800000
	s_waitcnt lgkmcnt(0)
	s_add_u32 s12, s2, s8
	s_addc_u32 s13, s3, s7
	s_ashr_i32 s7, s6, 31
	s_lshl_b64 s[8:9], s[6:7], 2
	s_add_u32 s8, s12, s8
	s_addc_u32 s9, s13, s9
	v_mov_b32_e32 v2, 0
	v_lshl_add_u64 v[28:29], s[8:9], 0, v[0:1]
	s_mov_b32 s8, 0
	v_mov_b32_e32 v38, v36
	v_mov_b32_e32 v3, v2
	v_pk_mov_b32 v[4:5], v[2:3], v[2:3] op_sel:[0,0]
	v_pk_mov_b32 v[6:7], v[2:3], v[2:3] op_sel:[0,0]
	v_pk_mov_b32 v[8:9], v[2:3], v[2:3] op_sel:[0,0]
	v_pk_mov_b32 v[10:11], v[2:3], v[2:3] op_sel:[0,0]
	v_pk_mov_b32 v[12:13], v[2:3], v[2:3] op_sel:[0,0]
	v_pk_mov_b32 v[14:15], v[2:3], v[2:3] op_sel:[0,0]
	v_pk_mov_b32 v[16:17], v[2:3], v[2:3] op_sel:[0,0]
	v_pk_mov_b32 v[18:19], v[2:3], v[2:3] op_sel:[0,0]
	v_pk_mov_b32 v[20:21], v[2:3], v[2:3] op_sel:[0,0]

.LBB0_120:
	v_lshlrev_b32_e32 v47, 16, v33
	v_lshlrev_b32_e32 v46, 16, v32
	v_and_b32_e32 v33, 0xffff0000, v33
	v_and_b32_e32 v32, 0xffff0000, v32
	v_pk_mul_f32 v[56:57], v[32:33], v[32:33]
	v_lshlrev_b32_e32 v44, 16, v30
	v_and_b32_e32 v45, 0xffff0000, v30
	v_lshlrev_b32_e32 v30, 16, v31
	v_pk_fma_f32 v[56:57], v[46:47], v[46:47], v[56:57]
	v_and_b32_e32 v31, 0xffff0000, v31
	v_lshlrev_b32_e32 v48, 16, v26
	v_and_b32_e32 v49, 0xffff0000, v26
	v_lshlrev_b32_e32 v52, 16, v28
	v_and_b32_e32 v64, 0xffff0000, v28
	v_mul_f32_e32 v26, v44, v44
	v_mul_f32_e32 v28, v30, v30
	v_pk_add_f32 v[56:57], v[56:57], v[56:57] op_sel_hi:[0,1]
	v_lshlrev_b32_e32 v50, 16, v27
	v_and_b32_e32 v51, 0xffff0000, v27
	v_lshlrev_b32_e32 v54, 16, v29
	v_and_b32_e32 v55, 0xffff0000, v29
	v_pk_fma_f32 v[26:27], v[44:45], v[44:45], v[26:27] op_sel_hi:[1,1,0]
	v_pk_fma_f32 v[28:29], v[30:31], v[30:31], v[28:29] op_sel_hi:[1,1,0]
	v_mul_f32_e32 v56, v48, v48
	v_pk_fma_f32 v[58:59], v[48:49], v[48:49], v[56:57] op_sel_hi:[1,1,0]
	v_mul_f32_e32 v56, v50, v50
	v_mov_b32_e32 v53, v27
	v_pk_mov_b32 v[62:63], v[52:53], v[28:29] op_sel:[0,1]
	v_pk_fma_f32 v[60:61], v[50:51], v[50:51], v[56:57] op_sel_hi:[1,1,0]
	v_pk_mul_f32 v[62:63], v[52:53], v[62:63]
	v_pk_add_f32 v[26:27], v[26:27], v[28:29]
	v_mul_f32_e32 v56, v64, v64
	v_mul_f32_e32 v58, v54, v54
	v_mul_f32_e32 v60, v55, v55
	v_mov_b32_e32 v63, v27
	v_pk_add_f32 v[26:27], v[62:63], v[56:57]
	v_pk_add_f32 v[28:29], v[58:59], v[60:61]
	s_nop 0
	v_pk_add_f32 v[26:27], v[26:27], v[28:29]
	s_nop 0
	v_add_f32_e32 v26, v26, v27
	ds_bpermute_b32 v27, v38, v26
	s_waitcnt lgkmcnt(0)
	v_add_f32_e32 v26, v26, v27
	ds_bpermute_b32 v27, v39, v26
	s_waitcnt lgkmcnt(0)
	v_add_f32_e32 v26, v26, v27
	ds_bpermute_b32 v27, v40, v26
	s_waitcnt lgkmcnt(0)
	v_add_f32_e32 v26, v26, v27
	ds_bpermute_b32 v27, v41, v26
	s_waitcnt lgkmcnt(0)
	v_add_f32_e32 v26, v26, v27
	ds_bpermute_b32 v27, v42, v26
	s_waitcnt lgkmcnt(0)
	v_add_f32_e32 v26, v26, v27
	ds_bpermute_b32 v27, v43, v26
	s_waitcnt lgkmcnt(0)
	v_add_f32_e32 v26, v26, v27
	v_fmamk_f32 v26, v26, 0x3a800000, v209
	v_mul_f32_e32 v27, 0x4f800000, v26
	v_cmp_gt_f32_e32 vcc, s23, v26
	s_nop 1
	v_cndmask_b32_e32 v26, v26, v27, vcc
	v_sqrt_f32_e32 v27, v26
	s_nop 0
	v_add_u32_e32 v28, -1, v27
	v_fma_f32 v29, -v28, v27, v26
	v_cmp_ge_f32_e64 s[42:43], 0, v29
	v_add_u32_e32 v29, 1, v27
	s_nop 0
	v_cndmask_b32_e64 v28, v27, v28, s[42:43]
	v_fma_f32 v27, -v29, v27, v26
	v_cmp_lt_f32_e64 s[42:43], 0, v27
	s_nop 1
	v_cndmask_b32_e64 v27, v28, v29, s[42:43]
	v_mul_f32_e32 v28, 0x37800000, v27
	v_cndmask_b32_e32 v27, v27, v28, vcc
	v_cmp_class_f32_e32 vcc, v26, v210
	s_nop 1
	v_cndmask_b32_e32 v26, v27, v26, vcc
	v_div_scale_f32 v27, s[12:13], v26, v26, 1.0
	v_rcp_f32_e32 v28, v27
	v_readlane_b32 s12, v254, 47
	v_readlane_b32 s13, v254, 48
	v_fma_f32 v29, -v27, v28, 1.0
	v_fmac_f32_e32 v28, v29, v28
	v_div_scale_f32 v29, vcc, 1.0, v26, 1.0
	v_mul_f32_e32 v53, v29, v28
	v_fma_f32 v56, -v27, v53, v29
	v_fmac_f32_e32 v53, v56, v28
	v_fma_f32 v27, -v27, v53, v29
	v_div_fmas_f32 v27, v27, v28, v53
	v_div_fixup_f32 v56, v27, v26, 1.0
	v_pk_mul_f32 v[26:27], v[56:57], v[44:45] op_sel_hi:[0,1]
	v_pk_mul_f32 v[28:29], v[56:57], v[30:31] op_sel_hi:[0,1]
	s_waitcnt vmcnt(2)
	v_pk_mul_f32 v[28:29], v[8:9], v[28:29]
	v_pk_mul_f32 v[26:27], v[6:7], v[26:27]
	v_lshl_add_u64 v[30:31], s[6:7], 0, v[34:35]
	global_store_dwordx4 v[30:31], v[26:29], off
	v_lshl_add_u64 v[30:31], s[6:7], 0, v[0:1]
	v_mov_b32_e32 v53, v64
	v_pk_mov_b32 v[26:27], v[46:47], v[32:33] op_sel:[0,0]
	v_mov_b32_e32 v32, v47
	v_pk_mul_f32 v[26:27], v[56:57], v[26:27] op_sel_hi:[0,1]
	v_pk_mul_f32 v[28:29], v[56:57], v[32:33] op_sel_hi:[0,1]
	v_pk_mul_f32 v[28:29], v[4:5], v[28:29]
	v_pk_mul_f32 v[26:27], v[2:3], v[26:27]
	global_store_dwordx4 v[30:31], v[26:29], off offset:16
	s_add_u32 s6, s6, s12
	s_addc_u32 s7, s7, s13
	v_pk_mul_f32 v[26:27], v[56:57], v[48:49] op_sel_hi:[0,1]
	v_pk_mul_f32 v[28:29], v[56:57], v[50:51] op_sel_hi:[0,1]
	s_waitcnt vmcnt(2)
	v_pk_mul_f32 v[28:29], v[16:17], v[28:29]
	v_pk_mul_f32 v[26:27], v[14:15], v[26:27]
	global_store_dwordx4 v[30:31], v[26:29], off offset:2048
	v_readlane_b32 s12, v254, 49
	v_readlane_b32 s13, v254, 50
	v_pk_mul_f32 v[26:27], v[52:53], v[56:57] op_sel_hi:[1,0]
	v_pk_mul_f32 v[28:29], v[54:55], v[56:57] op_sel_hi:[1,0]
	v_pk_mul_f32 v[26:27], v[10:11], v[26:27]
	v_pk_mul_f32 v[28:29], v[12:13], v[28:29]
	global_store_dwordx4 v[30:31], v[26:29], off offset:2064
	v_mov_b64_e32 v[32:33], v[20:21]
	v_lshl_add_u64 v[36:37], v[36:37], 0, s[12:13]
	v_mov_b64_e32 v[28:29], v[24:25]
	s_and_b64 vcc, exec, s[8:9]
	v_mov_b64_e32 v[30:31], v[18:19]
	v_mov_b64_e32 v[26:27], v[22:23]
	s_cbranch_vccnz .LBB0_123

.LBB0_156:
	s_waitcnt vmcnt(0)
	v_mov_b32_e32 v60, v1
	v_mov_b32_e32 v61, v1
	v_pk_mov_b32 v[58:59], v[0:1], v[0:1] op_sel:[1,1]
	v_mov_b64_e32 v[64:65], v[60:61]
	v_mov_b64_e32 v[62:63], v[58:59]
	s_andn2_b64 vcc, exec, s[12:13]
	s_cbranch_vccnz .LBB0_169

.LBB0_164:
	s_cmpk_lt_i32 s12, 0x4000
	s_cselect_b64 s[2:3], -1, 0
	s_or_b64 s[2:3], s[10:11], s[2:3]
	v_lshlrev_b32_e32 v82, 16, v58
	v_and_b32_e32 v83, 0xffff0000, v58
	v_lshlrev_b32_e32 v84, 16, v59
	v_and_b32_e32 v85, 0xffff0000, v59
	v_lshlrev_b32_e32 v78, 16, v60
	v_and_b32_e32 v79, 0xffff0000, v60
	v_lshlrev_b32_e32 v80, 16, v61
	v_and_b32_e32 v81, 0xffff0000, v61
	v_lshlrev_b32_e32 v76, 16, v62
	v_and_b32_e32 v77, 0xffff0000, v62
	v_lshlrev_b32_e32 v62, 16, v63
	v_and_b32_e32 v63, 0xffff0000, v63
	v_lshlrev_b32_e32 v58, 16, v64
	v_and_b32_e32 v59, 0xffff0000, v64
	v_lshlrev_b32_e32 v60, 16, v65
	v_and_b32_e32 v61, 0xffff0000, v65
	s_and_b64 vcc, exec, s[2:3]
	s_cbranch_vccnz .LBB0_159
	s_lshl_b64 s[2:3], s[20:21], 12
	v_mov_b32_e32 v92, 0
	v_lshl_add_u64 v[104:105], v[72:73], 0, s[2:3]
	v_lshl_add_u64 v[102:103], v[70:71], 0, s[2:3]
	s_mov_b32 s2, 0
	v_mov_b32_e32 v93, v92
	v_mov_b32_e32 v96, v92
	v_mov_b32_e32 v97, v92
	v_pk_mov_b32 v[94:95], v[92:93], v[92:93] op_sel:[0,0]
	v_pk_mov_b32 v[98:99], v[92:93], v[92:93] op_sel:[0,0]
	v_pk_mov_b32 v[64:65], v[92:93], v[92:93] op_sel:[0,0]
	v_pk_mov_b32 v[88:89], v[92:93], v[92:93] op_sel:[0,0]
	v_pk_mov_b32 v[86:87], v[92:93], v[92:93] op_sel:[0,0]
	v_pk_mov_b32 v[90:91], v[92:93], v[92:93] op_sel:[0,0]

.LBB0_231:
	v_mul_hi_u32 v0, v2, s95
	v_lshrrev_b32_e32 v6, 7, v0
	s_movk_i32 s16, 0xb0
	v_mul_lo_u32 v0, v6, s16
	v_sub_u32_e32 v8, v2, v0
	v_lshlrev_b32_e32 v0, 3, v8
	v_lshl_add_u64 v[2:3], v[2:3], 0, s[66:67]
	s_mov_b64 s[18:19], 0x2ec000
	v_mad_u64_u32 v[4:5], s[14:15], v6, s94, v[0:1]
	v_mov_b64_e32 v[10:11], s[6:7]
	v_cmp_gt_u64_e64 s[44:45], s[18:19], v[2:3]
	v_mad_u64_u32 v[6:7], s[14:15], v6, s91, v[10:11]
	v_lshlrev_b32_e32 v0, 4, v8
	v_lshlrev_b64 v[4:5], 1, v[4:5]
	v_cndmask_b32_e64 v9, v172, v2, s[44:45]
	v_lshl_add_u64 v[6:7], v[6:7], 0, v[0:1]
	s_waitcnt vmcnt(0)
	v_lshl_add_u64 v[58:59], s[8:9], 0, v[4:5]
	v_lshl_add_u64 v[4:5], s[10:11], 0, v[4:5]
	v_cndmask_b32_e64 v8, v173, v3, s[44:45]
	v_mul_hi_u32 v0, v9, s95
	global_load_dwordx4 v[26:29], v[6:7], off
	global_load_dwordx4 v[38:41], v[58:59], off
	global_load_dwordx4 v[42:45], v[4:5], off
	v_mad_u64_u32 v[4:5], s[14:15], v8, s95, v[0:1]
	v_mov_b32_e32 v0, v5
	v_mov_b32_e32 v5, v1
	s_mov_b32 s17, 0x2e8ba2e8
	v_mad_u64_u32 v[4:5], s[14:15], v9, s17, v[4:5]
	v_mov_b32_e32 v4, v5
	v_mov_b32_e32 v5, v1
	v_lshl_add_u64 v[4:5], v[0:1], 0, v[4:5]
	v_mad_u64_u32 v[4:5], s[14:15], v8, s17, v[4:5]
	v_alignbit_b32 v12, v5, v4, 5
	v_mad_u64_u32 v[6:7], s[14:15], v12, s16, 0
	v_mov_b32_e32 v0, v7
	v_lshrrev_b32_e32 v13, 5, v5
	v_mad_u64_u32 v[4:5], s[14:15], v13, s16, v[0:1]
	v_sub_co_u32_e32 v6, vcc, v9, v6
	v_lshl_add_u64 v[2:3], v[2:3], 0, s[66:67]
	s_nop 0
	v_subb_co_u32_e32 v7, vcc, v8, v4, vcc
	v_lshlrev_b64 v[4:5], 3, v[6:7]
	v_mad_u64_u32 v[4:5], s[14:15], v12, s94, v[4:5]
	v_mov_b32_e32 v0, v5
	v_mad_u64_u32 v[8:9], s[14:15], v13, s94, v[0:1]
	v_mov_b32_e32 v5, v8
	v_mad_u64_u32 v[8:9], s[14:15], v12, s91, v[10:11]
	v_mov_b32_e32 v0, v9
	v_mad_u64_u32 v[12:13], s[14:15], v13, s91, v[0:1]
	v_mov_b32_e32 v9, v12
	v_cmp_gt_u64_e64 s[42:43], s[18:19], v[2:3]
	v_lshl_add_u64 v[6:7], v[6:7], 4, v[8:9]
	v_lshlrev_b64 v[4:5], 1, v[4:5]
	v_cndmask_b32_e64 v9, v172, v2, s[42:43]
	v_lshl_add_u64 v[36:37], s[8:9], 0, v[4:5]
	v_lshl_add_u64 v[4:5], s[10:11], 0, v[4:5]
	v_cndmask_b32_e64 v8, v173, v3, s[42:43]
	v_mul_hi_u32 v0, v9, s95
	global_load_dwordx4 v[46:49], v[6:7], off
	global_load_dwordx4 v[50:53], v[4:5], off
	v_mad_u64_u32 v[4:5], s[14:15], v8, s95, v[0:1]
	v_mov_b32_e32 v0, v5
	v_mov_b32_e32 v5, v1
	v_mad_u64_u32 v[4:5], s[14:15], v9, s17, v[4:5]
	v_pk_mov_b32 v[4:5], v[4:5], v[0:1] op_sel:[1,1]
	v_lshl_add_u64 v[4:5], v[0:1], 0, v[4:5]
	v_mad_u64_u32 v[4:5], s[14:15], v8, s17, v[4:5]
	v_alignbit_b32 v12, v5, v4, 5
	v_mad_u64_u32 v[6:7], s[14:15], v12, s16, 0
	v_mov_b32_e32 v0, v7
	v_lshrrev_b32_e32 v13, 5, v5
	v_mad_u64_u32 v[4:5], s[14:15], v13, s16, v[0:1]
	v_sub_co_u32_e32 v6, vcc, v9, v6
	v_lshl_add_u64 v[30:31], v[2:3], 0, s[66:67]
	s_nop 0
	v_subb_co_u32_e32 v7, vcc, v8, v4, vcc
	v_lshlrev_b64 v[4:5], 3, v[6:7]
	v_mad_u64_u32 v[4:5], s[14:15], v12, s94, v[4:5]
	v_mov_b32_e32 v0, v5
	v_mad_u64_u32 v[8:9], s[14:15], v13, s94, v[0:1]
	v_mov_b32_e32 v5, v8
	v_mad_u64_u32 v[8:9], s[14:15], v12, s91, v[10:11]
	v_mov_b32_e32 v0, v9
	v_mad_u64_u32 v[12:13], s[14:15], v13, s91, v[0:1]
	v_cmp_gt_u64_e32 vcc, s[18:19], v[30:31]
	v_lshlrev_b64 v[4:5], 1, v[4:5]
	v_mov_b32_e32 v9, v12
	v_cndmask_b32_e32 v13, v172, v30, vcc
	v_lshl_add_u64 v[34:35], s[8:9], 0, v[4:5]
	global_load_dwordx4 v[54:57], v[36:37], off
	global_load_dwordx4 v[14:17], v[34:35], off
	v_cndmask_b32_e32 v12, v173, v31, vcc
	v_mul_hi_u32 v0, v13, s95
	v_mad_u64_u32 v[2:3], s[14:15], v12, s95, v[0:1]
	v_mov_b32_e32 v0, v3
	v_mov_b32_e32 v3, v1
	v_mad_u64_u32 v[2:3], s[14:15], v13, s17, v[2:3]
	v_pk_mov_b32 v[2:3], v[2:3], v[0:1] op_sel:[1,1]
	v_lshl_add_u64 v[2:3], v[0:1], 0, v[2:3]
	v_mad_u64_u32 v[2:3], s[14:15], v12, s17, v[2:3]
	v_lshl_add_u64 v[6:7], v[6:7], 4, v[8:9]
	v_lshl_add_u64 v[4:5], s[10:11], 0, v[4:5]
	v_alignbit_b32 v18, v3, v2, 5
	global_load_dwordx4 v[6:9], v[6:7], off
	s_nop 0
	global_load_dwordx4 v[22:25], v[4:5], off
	v_mad_u64_u32 v[4:5], s[14:15], v18, s16, 0
	v_mov_b32_e32 v0, v5
	v_lshrrev_b32_e32 v19, 5, v3
	v_mad_u64_u32 v[2:3], s[14:15], v19, s16, v[0:1]
	v_sub_co_u32_e64 v4, s[46:47], v13, v4
	v_mad_u64_u32 v[10:11], s[14:15], v18, s91, v[10:11]
	s_nop 0
	v_subb_co_u32_e64 v5, s[46:47], v12, v2, s[46:47]
	v_lshlrev_b64 v[2:3], 3, v[4:5]
	v_mad_u64_u32 v[2:3], s[14:15], v18, s94, v[2:3]
	v_mov_b32_e32 v0, v3
	v_mad_u64_u32 v[12:13], s[14:15], v19, s94, v[0:1]
	v_mov_b32_e32 v0, v11
	v_mov_b32_e32 v3, v12
	v_mad_u64_u32 v[12:13], s[14:15], v19, s91, v[0:1]
	v_mov_b32_e32 v11, v12
	v_lshlrev_b64 v[2:3], 1, v[2:3]
	v_lshl_add_u64 v[4:5], v[4:5], 4, v[10:11]
	v_lshl_add_u64 v[32:33], s[8:9], 0, v[2:3]
	v_lshl_add_u64 v[18:19], s[10:11], 0, v[2:3]
	global_load_dwordx4 v[10:13], v[32:33], off
	s_nop 0
	global_load_dwordx4 v[2:5], v[4:5], off
	s_nop 0
	global_load_dwordx4 v[18:21], v[18:19], off
	s_waitcnt vmcnt(10)
	v_lshlrev_b32_e32 v0, 16, v38
	s_waitcnt vmcnt(9)
	v_lshlrev_b32_e32 v60, 16, v42
	v_and_b32_e32 v42, 0xffff0000, v42
	v_and_b32_e32 v38, 0xffff0000, v38
	v_add_f32_e32 v0, v60, v0
	v_add_f32_e32 v38, v42, v38
	v_lshlrev_b32_e32 v42, 16, v26
	v_and_b32_e32 v26, 0xffff0000, v26
	v_mul_f32_e32 v0, v0, v42
	v_mul_f32_e32 v26, v38, v26
	v_cvt_pk_bf16_f32 v26, v0, v26
	v_lshlrev_b32_e32 v0, 16, v39
	v_lshlrev_b32_e32 v38, 16, v43
	v_add_f32_e32 v0, v38, v0
	v_and_b32_e32 v38, 0xffff0000, v43
	v_and_b32_e32 v39, 0xffff0000, v39
	v_add_f32_e32 v38, v38, v39
	v_lshlrev_b32_e32 v39, 16, v27
	v_and_b32_e32 v27, 0xffff0000, v27
	v_mul_f32_e32 v0, v0, v39
	v_mul_f32_e32 v27, v38, v27
	v_cvt_pk_bf16_f32 v27, v0, v27
	v_lshlrev_b32_e32 v0, 16, v40
	v_lshlrev_b32_e32 v38, 16, v44
	v_add_f32_e32 v0, v38, v0
	v_and_b32_e32 v38, 0xffff0000, v44
	v_and_b32_e32 v39, 0xffff0000, v40
	v_add_f32_e32 v38, v38, v39
	v_lshlrev_b32_e32 v39, 16, v28
	v_and_b32_e32 v28, 0xffff0000, v28
	v_mul_f32_e32 v0, v0, v39
	v_mul_f32_e32 v28, v38, v28
	v_cvt_pk_bf16_f32 v28, v0, v28
	v_lshlrev_b32_e32 v0, 16, v41
	v_lshlrev_b32_e32 v38, 16, v45
	v_add_f32_e32 v0, v38, v0
	v_and_b32_e32 v38, 0xffff0000, v45
	v_and_b32_e32 v39, 0xffff0000, v41
	v_add_f32_e32 v38, v38, v39
	v_lshlrev_b32_e32 v39, 16, v29
	v_and_b32_e32 v29, 0xffff0000, v29
	v_mul_f32_e32 v0, v0, v39
	v_mul_f32_e32 v29, v38, v29
	v_cvt_pk_bf16_f32 v29, v0, v29
	global_store_dwordx4 v[58:59], v[26:29], off
	s_waitcnt vmcnt(7)
	v_lshlrev_b32_e32 v0, 16, v54
	v_and_b32_e32 v38, 0xffff0000, v53
	v_lshlrev_b32_e32 v26, 16, v50
	v_add_f32_e32 v0, v0, v26
	v_and_b32_e32 v26, 0xffff0000, v54
	v_and_b32_e32 v27, 0xffff0000, v50
	v_add_f32_e32 v26, v26, v27
	v_lshlrev_b32_e32 v27, 16, v46
	v_mul_f32_e32 v0, v0, v27
	v_and_b32_e32 v27, 0xffff0000, v46
	v_mul_f32_e32 v26, v26, v27
	v_cvt_pk_bf16_f32 v26, v0, v26
	v_lshlrev_b32_e32 v0, 16, v55
	v_lshlrev_b32_e32 v27, 16, v51
	v_add_f32_e32 v0, v0, v27
	v_and_b32_e32 v27, 0xffff0000, v55
	v_and_b32_e32 v28, 0xffff0000, v51
	v_add_f32_e32 v27, v27, v28
	v_lshlrev_b32_e32 v28, 16, v47
	v_mul_f32_e32 v0, v0, v28
	v_and_b32_e32 v28, 0xffff0000, v47
	v_mul_f32_e32 v27, v27, v28
	v_cvt_pk_bf16_f32 v27, v0, v27
	v_lshlrev_b32_e32 v0, 16, v56
	v_lshlrev_b32_e32 v28, 16, v52
	v_add_f32_e32 v0, v0, v28
	v_and_b32_e32 v28, 0xffff0000, v56
	v_and_b32_e32 v29, 0xffff0000, v52
	v_add_f32_e32 v28, v28, v29
	v_lshlrev_b32_e32 v29, 16, v48
	v_mul_f32_e32 v0, v0, v29
	v_and_b32_e32 v29, 0xffff0000, v48
	v_mul_f32_e32 v28, v28, v29
	v_cvt_pk_bf16_f32 v28, v0, v28
	v_lshlrev_b32_e32 v0, 16, v57
	v_lshlrev_b32_e32 v29, 16, v53
	v_add_f32_e32 v0, v0, v29
	v_and_b32_e32 v29, 0xffff0000, v57
	v_add_f32_e32 v29, v29, v38
	v_lshlrev_b32_e32 v38, 16, v49
	v_mul_f32_e32 v0, v0, v38
	v_and_b32_e32 v38, 0xffff0000, v49
	v_mul_f32_e32 v29, v29, v38
	v_cvt_pk_bf16_f32 v29, v0, v29
	s_and_saveexec_b64 s[14:15], s[44:45]
	s_cbranch_execz .LBB0_233
	global_store_dwordx4 v[36:37], v[26:29], off

.LBB0_541:
	s_lshl_b64 s[10:11], s[10:11], 1
	s_add_u32 s10, s6, s10
	s_addc_u32 s11, s7, s11
	s_waitcnt vmcnt(0)
	v_lshlrev_b32_e32 v2, 1, v0
	global_load_dwordx4 v[74:77], v2, s[10:11]
	global_load_dwordx4 v[70:73], v2, s[10:11] offset:1024
	v_mov_b32_e32 v68, v1
	v_mov_b32_e32 v69, v1
	v_pk_mov_b32 v[66:67], v[0:1], v[0:1] op_sel:[1,1]
	v_mov_b64_e32 v[80:81], v[68:69]
	v_mov_b64_e32 v[78:79], v[66:67]

.LBB0_543:
	s_waitcnt vmcnt(0)
	v_mov_b32_e32 v2, v1
	v_mov_b32_e32 v3, v1
	v_pk_mov_b32 v[68:69], v[0:1], v[0:1] op_sel:[1,1]
	v_mov_b32_e32 v0, v1
	v_pk_mov_b32 v[66:67], v[0:1], v[0:1] op_sel:[1,1]
	v_mov_b64_e32 v[80:81], v[68:69]
	v_mov_b64_e32 v[72:73], v[2:3]
	v_mov_b64_e32 v[76:77], v[2:3]
	v_mov_b64_e32 v[78:79], v[66:67]
	v_mov_b64_e32 v[70:71], v[0:1]
	v_mov_b64_e32 v[74:75], v[0:1]
	s_load_dwordx2 s[10:11], s[0:1], 0x30
	s_andn2_b64 vcc, exec, s[8:9]
	s_cbranch_vccnz .LBB0_562

.LBB0_556:
	s_andn2_b64 vcc, exec, s[16:17]
	s_cbranch_vccnz .LBB0_558
	v_mov_b32_e32 v112, v74
	v_mov_b32_e32 v113, v75
	v_pk_mov_b32 v[116:117], v[76:77], v[76:77] op_sel:[0,1]
	v_pk_mov_b32 v[110:111], v[70:71], v[70:71] op_sel:[0,1]
	v_pk_mov_b32 v[114:115], v[72:73], v[72:73] op_sel:[0,1]
	v_pk_mov_b32 v[106:107], v[78:79], v[78:79] op_sel:[0,1]
	v_pk_mov_b32 v[108:109], v[80:81], v[80:81] op_sel:[0,1]
	v_pk_mov_b32 v[102:103], v[66:67], v[66:67] op_sel:[0,1]
	v_pk_mov_b32 v[104:105], v[68:69], v[68:69] op_sel:[0,1]

.LBB0_564:
	s_waitcnt vmcnt(0)
	v_mov_b32_e32 v34, v208
	s_lshl_b32 s8, s13, 3
	s_and_b32 s8, s8, 0xffffff80
	s_load_dwordx2 s[14:15], s[0:1], 0x80
	v_and_b32_e32 v84, 15, v34
	v_ashrrev_i32_e32 v85, 4, v34
	v_lshlrev_b32_e32 v0, 4, v84
	v_lshl_add_u64 v[6:7], s[6:7], 0, v[0:1]
	v_add_u32_e32 v2, s8, v85
	v_mov_b32_e32 v3, 0
	v_lshlrev_b64 v[2:3], 8, v[2:3]
	v_lshl_add_u64 v[2:3], v[6:7], 0, v[2:3]
	global_load_dwordx4 v[52:55], v[2:3], off
	v_add_co_u32_e32 v2, vcc, 0x2000, v2
	s_nop 1
	v_addc_co_u32_e32 v3, vcc, 0, v3, vcc
	global_load_dwordx4 v[56:59], v[2:3], off
	v_add_co_u32_e32 v2, vcc, 0x2000, v2
	s_nop 1
	v_addc_co_u32_e32 v3, vcc, 0, v3, vcc
	global_load_dwordx4 v[60:63], v[2:3], off
	v_add_co_u32_e32 v2, vcc, 0x2000, v2
	s_nop 1
	v_addc_co_u32_e32 v3, vcc, 0, v3, vcc
	global_load_dwordx4 v[64:67], v[2:3], off
	s_lshl_b32 s9, s13, 7
	s_and_b32 s9, s9, 0x780
	v_and_b32_e32 v86, 31, v34
	v_lshlrev_b32_e32 v0, 4, v86
	s_waitcnt lgkmcnt(0)
	s_add_u32 s14, s14, s2
	s_addc_u32 s15, s15, s3
	s_lshl_b32 s16, s9, 2
	s_add_u32 s14, s14, s16
	s_addc_u32 s15, s15, 0
	v_lshl_add_u64 v[8:9], s[14:15], 0, v[0:1]
	v_ashrrev_i32_e32 v2, 5, v34
	v_mov_b32_e32 v3, 0
	v_lshlrev_b64 v[2:3], 13, v[2:3]
	v_lshl_add_u64 v[2:3], v[8:9], 0, v[2:3]
	global_load_dwordx4 v[68:71], v[2:3], off
	v_add_co_u32_e32 v2, vcc, 0x20000, v2
	s_nop 1
	v_addc_co_u32_e32 v3, vcc, 0, v3, vcc
	global_load_dwordx4 v[72:75], v[2:3], off
	v_add_co_u32_e32 v2, vcc, 0x20000, v2
	s_nop 1
	v_addc_co_u32_e32 v3, vcc, 0, v3, vcc
	global_load_dwordx4 v[76:79], v[2:3], off
	v_add_co_u32_e32 v2, vcc, 0x20000, v2
	s_nop 1
	v_addc_co_u32_e32 v3, vcc, 0, v3, vcc
	global_load_dwordx4 v[80:83], v[2:3], off
	v_mul_u32_u24_e32 v87, 0x840, v84
	v_lshl_add_u32 v87, v85, 2, v87
	v_add_u32_e32 v88, 0x400, v87
	v_ashrrev_i32_e32 v89, 5, v34
	v_lshlrev_b32_e32 v89, 9, v89
	v_lshl_add_u32 v89, v86, 4, v89
	s_waitcnt vmcnt(7)
	ds_write2_b32 v87, v52, v53 offset0:0 offset1:132
	ds_write2_b32 v88, v54, v55 offset0:8 offset1:140
	s_waitcnt vmcnt(6)
	ds_write2_b32 v87, v56, v57 offset0:32 offset1:164
	ds_write2_b32 v88, v58, v59 offset0:40 offset1:172
	s_waitcnt vmcnt(5)
	ds_write2_b32 v87, v60, v61 offset0:64 offset1:196
	ds_write2_b32 v88, v62, v63 offset0:72 offset1:204
	s_waitcnt vmcnt(4)
	ds_write2_b32 v87, v64, v65 offset0:96 offset1:228
	ds_write2_b32 v88, v66, v67 offset0:104 offset1:236
	s_waitcnt vmcnt(3)
	ds_write_b128 v89, v[68:71] offset:34816
	s_waitcnt vmcnt(2)
	ds_write_b128 v89, v[72:75] offset:43008
	s_waitcnt vmcnt(1)
	ds_write_b128 v89, v[76:79] offset:51200
	s_waitcnt vmcnt(0)
	ds_write_b128 v89, v[80:83] offset:59392
	s_add_i32 s14, 0, 0x8800
	v_and_b32_e32 v2, 0xffffffe0, v34
	v_and_b32_e32 v0, 31, v34
	v_add_u32_e32 v36, s14, v2
	v_mov_b32_e32 v2, 0
	v_lshl_add_u32 v35, v0, 4, 0
	s_mov_b32 s14, 0
	v_mov_b32_e32 v3, v2
	v_mov_b32_e32 v4, v2
	v_mov_b32_e32 v5, v2
	v_pk_mov_b32 v[30:31], v[2:3], v[2:3] op_sel:[0,0]
	v_pk_mov_b32 v[32:33], v[2:3], v[2:3] op_sel:[0,0]
	v_pk_mov_b32 v[26:27], v[2:3], v[2:3] op_sel:[0,0]
	v_pk_mov_b32 v[28:29], v[2:3], v[2:3] op_sel:[0,0]
	v_pk_mov_b32 v[22:23], v[2:3], v[2:3] op_sel:[0,0]
	v_pk_mov_b32 v[24:25], v[2:3], v[2:3] op_sel:[0,0]
	v_pk_mov_b32 v[18:19], v[2:3], v[2:3] op_sel:[0,0]
	v_pk_mov_b32 v[20:21], v[2:3], v[2:3] op_sel:[0,0]
	v_pk_mov_b32 v[14:15], v[2:3], v[2:3] op_sel:[0,0]
	v_pk_mov_b32 v[16:17], v[2:3], v[2:3] op_sel:[0,0]
	v_pk_mov_b32 v[10:11], v[2:3], v[2:3] op_sel:[0,0]
	v_pk_mov_b32 v[12:13], v[2:3], v[2:3] op_sel:[0,0]
	v_pk_mov_b32 v[6:7], v[2:3], v[2:3] op_sel:[0,0]
	v_pk_mov_b32 v[8:9], v[2:3], v[2:3] op_sel:[0,0]
	s_waitcnt lgkmcnt(0)
	s_barrier
	v_add_u32_e32 v37, s14, v36
	ds_read_b128 v[38:41], v35
	ds_read_b128 v[42:45], v37
	ds_read_b128 v[46:49], v37 offset:16
